# v84 + attention: waves 4-7 swap query halves (one wave of each half per SIMD), padded so that all later code keeps its byte placement
# baseline (speedup 1.0000x reference)
.LBB0_300:
	s_cmp_lt_i32 s90, 4
	s_cselect_b64 s[4:5], -1, 0
	s_and_b64 s[0:1], s[4:5], s[2:3]
	s_andn2_b64 vcc, exec, s[0:1]
	s_cbranch_vccnz .LBB0_353
	v_writelane_b32 v254, s4, 32
	v_bfe_u32 v186, v248, 8, 1
	v_lshlrev_b32_e32 v186, 6, v186
	v_xor_b32_e32 v186, v186, v248
	s_nop 0
	s_nop 0
	v_writelane_b32 v254, s5, 33
	v_and_b32_e32 v187, 63, v186
	v_readlane_b32 s0, v254, 16
	v_lshlrev_b32_e32 v0, 2, v187
	v_readlane_b32 s6, v254, 22
	v_readlane_b32 s7, v254, 23
	v_readlane_b32 s8, v254, 24
	v_readlane_b32 s9, v254, 25
	s_nop 2
	global_load_dword v2, v0, s[6:7]
	s_nop 0
	global_load_dword v3, v0, s[8:9]
	v_mbcnt_lo_u32_b32 v0, -1, 0
	v_mbcnt_hi_u32_b32 v9, -1, v0
	v_and_b32_e32 v0, 64, v9
	v_xor_b32_e32 v1, 1, v9
	v_add_u32_e32 v13, 64, v0
	v_cmp_lt_i32_e32 vcc, v1, v13
	v_xor_b32_e32 v4, 2, v9
	v_xor_b32_e32 v5, 4, v9
	v_cndmask_b32_e32 v0, v9, v1, vcc
	v_cmp_lt_i32_e32 vcc, v4, v13
	v_lshlrev_b32_e32 v1, 2, v0
	v_xor_b32_e32 v10, 8, v9
	v_cndmask_b32_e32 v6, v9, v4, vcc
	v_lshlrev_b32_e32 v0, 2, v6
	v_cmp_lt_i32_e32 vcc, v5, v13
	v_xor_b32_e32 v11, 16, v9
	v_xor_b32_e32 v12, 32, v9
	s_mov_b32 s0, 0x42700000
	v_readlane_b32 s2, v254, 18
	v_readlane_b32 s3, v254, 19
	v_readlane_b32 s1, v254, 17
	v_readlane_b32 s4, v254, 20
	v_readlane_b32 s5, v254, 21
	v_readlane_b32 s10, v254, 26
	v_readlane_b32 s11, v254, 27
	v_readlane_b32 s12, v254, 28
	v_readlane_b32 s13, v254, 29
	v_readlane_b32 s14, v254, 30
	v_readlane_b32 s15, v254, 31
	s_waitcnt vmcnt(0)
	v_and_b32_e32 v8, 0x7fffffff, v2
	v_and_b32_e32 v4, 0x7fffffff, v3
	ds_bpermute_b32 v14, v1, v8
	ds_bpermute_b32 v15, v1, v4
	v_max_f32_e64 v6, |v2|, |v2|
	v_max_f32_e64 v7, |v3|, |v3|
	s_waitcnt lgkmcnt(1)
	v_max_f32_e32 v2, v14, v14
	s_waitcnt lgkmcnt(0)
	v_max_f32_e32 v3, v15, v15
	v_max_f32_e32 v14, v6, v2
	v_max_f32_e32 v3, v7, v3
	ds_bpermute_b32 v15, v0, v14
	ds_bpermute_b32 v16, v0, v3
	v_cndmask_b32_e32 v2, v9, v5, vcc
	v_lshlrev_b32_e32 v2, 2, v2
	v_cmp_lt_i32_e32 vcc, v10, v13
	s_waitcnt lgkmcnt(1)
	v_max_f32_e32 v5, v15, v15
	s_waitcnt lgkmcnt(0)
	v_max_f32_e32 v15, v16, v16
	v_max_f32_e32 v5, v14, v5
	v_max_f32_e32 v14, v3, v15
	ds_bpermute_b32 v15, v2, v5
	ds_bpermute_b32 v16, v2, v14
	v_cndmask_b32_e32 v3, v9, v10, vcc
	v_lshlrev_b32_e32 v3, 2, v3
	v_cmp_lt_i32_e32 vcc, v11, v13
	s_waitcnt lgkmcnt(1)
	v_max_f32_e32 v10, v15, v15
	s_waitcnt lgkmcnt(0)
	v_max_f32_e32 v15, v16, v16
	v_max_f32_e32 v10, v5, v10
	v_max_f32_e32 v14, v14, v15
	ds_bpermute_b32 v15, v3, v10
	ds_bpermute_b32 v16, v3, v14
	v_cndmask_b32_e32 v5, v9, v11, vcc
	v_lshlrev_b32_e32 v5, 2, v5
	v_cmp_lt_i32_e32 vcc, v12, v13
	s_waitcnt lgkmcnt(1)
	v_max_f32_e32 v11, v15, v15
	s_waitcnt lgkmcnt(0)
	v_max_f32_e32 v15, v16, v16
	v_max_f32_e32 v10, v10, v11
	v_max_f32_e32 v11, v14, v15
	ds_bpermute_b32 v14, v5, v10
	ds_bpermute_b32 v15, v5, v11
	v_cndmask_b32_e32 v9, v9, v12, vcc
	v_lshlrev_b32_e32 v192, 2, v9
	s_waitcnt lgkmcnt(1)
	v_max_f32_e32 v9, v14, v14
	s_waitcnt lgkmcnt(0)
	v_max_f32_e32 v12, v15, v15
	v_max_f32_e32 v9, v10, v9
	v_max_f32_e32 v10, v11, v12
	ds_bpermute_b32 v11, v192, v9
	ds_bpermute_b32 v12, v192, v10
	s_waitcnt lgkmcnt(1)
	v_max_f32_e32 v11, v11, v11
	s_waitcnt lgkmcnt(0)
	v_max_f32_e32 v12, v12, v12
	v_max_f32_e32 v9, v9, v11
	v_max_f32_e32 v10, v10, v12
	v_mul_f32_e32 v9, 0x413c5bb7, v9
	v_mul_f32_e32 v9, v10, v9
	v_cmp_gt_f32_e32 vcc, s0, v9
	s_nop 1
	v_cndmask_b32_e64 v9, 0, 1, vcc
	s_nop 0
	v_readfirstlane_b32 s0, v9
	s_and_b32 s0, s0, 1
	s_add_u32 s2, s88, 0x16000000
	s_addc_u32 s3, s89, 0
	s_cmp_eq_u32 s0, 0
	s_mov_b64 s[0:1], -1
	s_cbranch_scc0 .LBB0_327
	ds_bpermute_b32 v8, v1, v8
	ds_bpermute_b32 v1, v1, v4
	v_writelane_b32 v254, s94, 34
	v_writelane_b32 v255, s81, 5
	s_cmpk_gt_i32 s81, 0x8ff
	s_waitcnt lgkmcnt(1)
	v_max_f32_e32 v4, v8, v8
	s_waitcnt lgkmcnt(0)
	v_max_f32_e32 v1, v1, v1
	v_max_f32_e32 v4, v6, v4
	v_max_f32_e32 v1, v7, v1
	ds_bpermute_b32 v6, v0, v4
	ds_bpermute_b32 v0, v0, v1
	v_writelane_b32 v254, s95, 35
	v_writelane_b32 v254, s93, 36
	v_writelane_b32 v254, s92, 37
	s_waitcnt lgkmcnt(1)
	v_max_f32_e32 v6, v6, v6
	s_waitcnt lgkmcnt(0)
	v_max_f32_e32 v0, v0, v0
	v_max_f32_e32 v4, v4, v6
	v_max_f32_e32 v0, v1, v0
	ds_bpermute_b32 v1, v2, v4
	ds_bpermute_b32 v2, v2, v0
	v_writelane_b32 v254, s86, 38
	v_readfirstlane_b32 s0, v186
	s_waitcnt lgkmcnt(1)
	v_max_f32_e32 v1, v1, v1
	s_waitcnt lgkmcnt(0)
	v_max_f32_e32 v2, v2, v2
	v_max_f32_e32 v1, v4, v1
	v_max_f32_e32 v0, v0, v2
	ds_bpermute_b32 v2, v3, v1
	ds_bpermute_b32 v3, v3, v0
	v_writelane_b32 v254, s87, 39
	v_writelane_b32 v254, s88, 49
	s_waitcnt lgkmcnt(1)
	v_max_f32_e32 v2, v2, v2
	s_waitcnt lgkmcnt(0)
	v_max_f32_e32 v3, v3, v3
	v_max_f32_e32 v1, v1, v2
	v_max_f32_e32 v0, v0, v3
	ds_bpermute_b32 v2, v5, v1
	ds_bpermute_b32 v3, v5, v0
	v_writelane_b32 v254, s89, 50
	v_writelane_b32 v254, s90, 51
	v_writelane_b32 v254, s91, 52
	s_waitcnt lgkmcnt(1)
	v_max_f32_e32 v2, v2, v2
	s_waitcnt lgkmcnt(0)
	v_max_f32_e32 v3, v3, v3
	v_max_f32_e32 v1, v1, v2
	v_max_f32_e32 v0, v0, v3
	ds_bpermute_b32 v3, v192, v1
	ds_bpermute_b32 v2, v192, v0
	v_writelane_b32 v254, s84, 40
	s_nop 1
	v_writelane_b32 v254, s85, 41
	s_cbranch_scc1 .LBB0_326
	v_readlane_b32 s4, v254, 40
	v_readlane_b32 s5, v254, 41
	s_cmpk_eq_i32 s4, 0x100
	s_cselect_b64 s[4:5], -1, 0
	s_ashr_i32 s1, s0, 7
	v_writelane_b32 v254, s4, 42
	s_and_b32 s8, s0, 64
	s_lshl_b32 s0, s1, 6
	v_writelane_b32 v254, s5, 43
	s_and_b32 s0, s0, 0xc0
	v_writelane_b32 v254, s1, 44
	s_add_u32 s0, s2, s0
	s_waitcnt lgkmcnt(1)
	v_max_f32_e32 v3, v3, v3
	v_max_f32_e32 v1, v1, v1
	v_writelane_b32 v254, s0, 45
	s_addc_u32 s0, s3, 0
	v_max_f32_e32 v1, v1, v3
	s_waitcnt lgkmcnt(0)
	v_max_f32_e32 v2, v2, v2
	v_max_f32_e32 v0, v0, v0
	v_writelane_b32 v254, s0, 46
	v_cmp_gt_u32_e64 s[0:1], 32, v187
	v_max_f32_e32 v0, v0, v2
	v_mul_f32_e32 v1, 0x413c5bb7, v1
	v_writelane_b32 v254, s0, 47
	v_mul_f32_e32 v188, v0, v1
	v_and_b32_e32 v1, 7, v186
	v_ashrrev_i32_e32 v170, 3, v186
	v_writelane_b32 v254, s1, 48
	s_movk_i32 s0, 0x90
	v_lshrrev_b32_e32 v6, 5, v187
	v_lshlrev_b32_e32 v4, 3, v1
	v_lshlrev_b32_e32 v1, 4, v1
	v_mul_lo_u32 v7, v170, s0
	v_readlane_b32 s4, v254, 49
	v_and_b32_e32 v168, 31, v186
	v_lshrrev_b32_e32 v3, 2, v186
	v_mov_b32_e32 v173, 0
	v_lshlrev_b32_e32 v172, 3, v6
	v_add3_u32 v189, 0, v1, v7
	v_lshl_add_u32 v1, v6, 4, 0
	v_lshlrev_b32_e32 v6, 2, v6
	v_readlane_b32 s5, v254, 50
	v_sub_u32_e32 v8, v168, v6
	v_and_or_b32 v3, v3, 3, v6
	v_lshl_add_u64 v[6:7], s[4:5], 0, v[172:173]
	s_mov_b64 s[0:1], 0xd000000
	v_lshl_add_u64 v[174:175], v[6:7], 0, s[0:1]
	v_cmp_lt_i32_e64 s[0:1], -1, v8
	v_readlane_b32 s6, v254, 51
	v_readlane_b32 s7, v254, 52
	v_writelane_b32 v254, s0, 53
	v_and_b32_e32 v5, 16, v186
	v_lshlrev_b32_e32 v2, 3, v186
	v_writelane_b32 v254, s1, 54
	v_cmp_gt_i32_e64 s[0:1], 1, v8
	v_lshlrev_b32_e32 v0, 5, v186
	v_and_b32_e32 v2, 24, v2
	v_writelane_b32 v254, s0, 55
	v_lshlrev_b32_e32 v5, 1, v5
	v_and_b32_e32 v0, 0x80, v0
	v_writelane_b32 v254, s1, 56
	v_cmp_lt_i32_e64 s[0:1], 0, v8
	v_add3_u32 v5, 0, v5, v2
	v_mul_u32_u24_e32 v6, 0x90, v168
	v_writelane_b32 v254, s0, 57
	v_mul_u32_u24_e32 v3, 0x90, v3
	s_mov_b32 s9, 0
	v_writelane_b32 v254, s1, 58
	v_cmp_gt_i32_e64 s[0:1], 2, v8
	v_mov_b32_e32 v169, v173
	v_ashrrev_i32_e32 v171, 31, v170
	v_writelane_b32 v254, s0, 59
	v_cmp_gt_i32_e64 s[18:19], 4, v8
	v_cmp_lt_i32_e64 s[24:25], 7, v8
	v_writelane_b32 v254, s1, 60
	v_cmp_lt_i32_e64 s[0:1], 1, v8
	v_cmp_gt_i32_e64 s[94:95], 9, v8
	v_cmp_lt_i32_e64 s[96:97], 8, v8
	v_writelane_b32 v254, s0, 61
	v_cmp_gt_i32_e64 s[92:93], 10, v8
	v_cmp_lt_i32_e64 s[28:29], 9, v8
	v_writelane_b32 v254, s1, 62
	v_cmp_gt_i32_e64 s[0:1], 3, v8
	v_cmp_gt_i32_e64 s[30:31], 11, v8
	v_cmp_lt_i32_e64 s[34:35], 10, v8
	v_writelane_b32 v254, s0, 63
	v_cmp_gt_i32_e64 s[36:37], 12, v8
	v_cmp_lt_i32_e64 s[38:39], 15, v8
	v_writelane_b32 v255, s1, 0
	v_cmp_lt_i32_e64 s[0:1], 2, v8
	v_cmp_gt_i32_e64 s[40:41], 17, v8
	v_cmp_lt_i32_e64 s[42:43], 16, v8
	v_writelane_b32 v255, s0, 1
	v_cmp_gt_i32_e64 s[44:45], 18, v8
	v_cmp_lt_i32_e64 s[46:47], 17, v8
	v_writelane_b32 v255, s1, 2
	v_writelane_b32 v255, s8, 3
	s_sub_i32 s0, 0xfffffe80, s8
	v_writelane_b32 v255, s0, 4
	v_cmp_gt_i32_e64 s[48:49], 19, v8
	v_cmp_lt_i32_e64 s[50:51], 18, v8
	v_cmp_gt_i32_e64 s[52:53], 20, v8
	v_cmp_lt_i32_e64 s[54:55], 23, v8
	v_cmp_gt_i32_e64 s[56:57], 25, v8
	v_cmp_lt_i32_e64 s[58:59], 24, v8
	v_cmp_gt_i32_e64 s[60:61], 26, v8
	v_cmp_lt_i32_e64 s[62:63], 25, v8
	v_cmp_gt_i32_e64 s[64:65], 27, v8
	v_cmp_lt_i32_e64 s[66:67], 26, v8
	v_cmp_gt_i32_e64 s[68:69], 28, v8
	s_movk_i32 s33, 0xc00
	v_lshlrev_b32_e32 v176, 1, v172
	v_lshlrev_b32_e32 v178, 1, v4
	v_lshlrev_b32_e32 v172, 1, v0
	v_lshlrev_b32_e32 v180, 1, v2
	v_add_u32_e32 v190, v1, v6
	v_add_u32_e32 v191, v5, v3
	v_mov_b32_e32 v177, v173
	v_mov_b32_e32 v193, 0xf149f2ca
	v_readlane_b32 s10, v255, 5
	s_branch .LBB0_305
